# attention: running row sums accumulated on the matrix core (16x16x32 bf16 MFMA of P against a 0/1 selector, f32 accumulate) instead of VALU adds
# speedup vs baseline: 1.0225x; 1.0225x over previous
.LBB0_765:
	s_mul_i32 s0, s36, 0x1dc0000
	s_mul_hi_i32 s1, s36, 0x1dc0000
	s_add_u32 s0, s24, s0
	s_addc_u32 s1, s25, s1
	s_lshl_b32 s6, s4, 6
	s_and_b32 s33, s6, 0xc0
	s_lshl_b32 s22, s33, 1
	s_cmp_lt_u32 s5, 2
	v_mov_b32_e32 v18, v222
	s_cselect_b32 s38, 4, 0x44
	v_lshlrev_b32_e32 v0, 4, v18
	s_add_u32 s6, s0, s22
	v_and_b32_e32 v4, 0x70, v0
	v_mov_b32_e32 v5, v3
	s_addc_u32 s7, s1, 0
	v_lshl_add_u64 v[0:1], s[6:7], 0, v[4:5]
	s_mov_b64 s[6:7], 0x1600
	v_ashrrev_i32_e32 v19, 3, v18
	v_lshl_add_u64 v[6:7], v[0:1], 0, s[6:7]
	s_mov_b64 s[6:7], 0x1800
	v_lshl_add_u64 v[0:1], v[0:1], 0, s[6:7]
	v_add_u32_e32 v2, 32, v19
	v_mad_i64_i32 v[10:11], s[6:7], v19, s48, v[0:1]
	v_mad_i64_i32 v[12:13], s[6:7], v2, s48, v[0:1]
	v_ashrrev_i32_e32 v0, 1, v18
	v_and_b32_e32 v0, 0xffffffe0, v0
	v_and_b32_e32 v5, 31, v18
	v_lshl_add_u32 v0, s5, 7, v0
	v_or_b32_e32 v148, v0, v5
	v_mov_b64_e32 v[0:1], s[0:1]
	v_bfe_u32 v219, v18, 5, 1
	v_mad_i64_i32 v[0:1], s[0:1], v148, s48, v[0:1]
	v_mad_i64_i32 v[8:9], s[6:7], v19, s48, v[6:7]
	v_mad_i64_i32 v[6:7], s[6:7], v2, s48, v[6:7]
	v_lshl_add_u64 v[14:15], v[0:1], 0, s[22:23]
	v_lshlrev_b32_e32 v2, 4, v219
	v_lshl_add_u64 v[14:15], v[14:15], 0, v[2:3]
	s_mov_b64 s[0:1], 0x1400
	v_lshl_add_u64 v[16:17], v[14:15], 0, s[0:1]
	s_movk_i32 s0, 0x1000
	v_add_co_u32_e32 v14, vcc, s0, v14
	s_mov_b32 s0, 0x70000
	s_nop 0
	v_addc_co_u32_e32 v15, vcc, 0, v15, vcc
	global_load_dwordx4 v[100:103], v[8:9], off
	global_load_dwordx4 v[104:107], v[6:7], off
	v_add_co_u32_e32 v8, vcc, s0, v8
	global_load_dwordx4 v[112:115], v[10:11], off
	global_load_dwordx4 v[128:131], v[12:13], off
	v_addc_co_u32_e32 v9, vcc, 0, v9, vcc
	v_add_co_u32_e32 v6, vcc, s0, v6
	global_load_dwordx4 v[108:111], v[16:17], off offset:32
	global_load_dwordx4 v[116:119], v[16:17], off offset:64
	global_load_dwordx4 v[120:123], v[14:15], off offset:1024
	global_load_dwordx4 v[124:127], v[16:17], off offset:96
	v_addc_co_u32_e32 v7, vcc, 0, v7, vcc
	global_load_dwordx4 v[132:135], v[8:9], off
	global_load_dwordx4 v[136:139], v[6:7], off
	v_add_co_u32_e32 v6, vcc, s0, v10
	v_mul_u32_u24_e32 v5, 0x48, v5
	s_nop 0
	v_addc_co_u32_e32 v7, vcc, 0, v11, vcc
	v_add_co_u32_e32 v8, vcc, s0, v12
	s_movk_i32 s0, 0x90
	s_nop 0
	v_addc_co_u32_e32 v9, vcc, 0, v13, vcc
	global_load_dwordx4 v[140:143], v[6:7], off
	global_load_dwordx4 v[144:147], v[8:9], off
	v_lshrrev_b32_e32 v6, 3, v18
	v_bfe_u32 v7, v18, 2, 2
	v_mul_lo_u32 v9, v19, s0
	v_and_b32_e32 v8, 16, v18
	v_and_or_b32 v6, v6, 4, v7
	v_add3_u32 v239, 32, v9, v4
	v_lshlrev_b32_e32 v4, 2, v18
	v_lshlrev_b32_e32 v5, 1, v5
	v_and_or_b32 v4, v4, 12, v8
	v_add3_u32 v240, 32, v5, v2
	v_mul_u32_u24_e32 v5, 0x48, v6
	v_lshlrev_b32_e32 v4, 1, v4
	v_lshlrev_b32_e32 v5, 1, v5
	v_add3_u32 v241, 32, v4, v5
	v_add3_u32 v242, 32, v5, v4
	v_mad_i64_i32 v[4:5], s[0:1], v19, s48, 0
	v_mad_i64_i32 v[4:5], s[0:1], s36, v237, v[4:5]
	s_and_b32 s0, s4, 3
	v_and_b32_e32 v6, 7, v18
	s_lshl_b32 s0, s0, 7
	v_lshlrev_b32_e32 v6, 4, v6
	v_or3_b32 v4, v4, s0, v6
	v_mov_b32_e32 v18, v3
	v_mov_b32_e32 v19, v3
	v_lshl_add_u64 v[150:151], s[30:31], 0, v[4:5]
	v_mov_b32_e32 v4, v3
	v_mov_b32_e32 v5, v3
	v_mov_b32_e32 v6, v3
	v_mov_b32_e32 v7, v3
	v_mov_b32_e32 v8, v3
	v_mov_b32_e32 v9, v3
	v_mov_b32_e32 v10, v3
	v_mov_b32_e32 v11, v3
	v_mov_b32_e32 v12, v3
	v_mov_b32_e32 v13, v3
	v_mov_b32_e32 v14, v3
	v_mov_b32_e32 v15, v3
	v_mov_b32_e32 v16, v3
	v_mov_b32_e32 v17, v3
	s_waitcnt vmcnt(22)
	v_mov_b64_e32 v[34:35], v[18:19]
	s_waitcnt vmcnt(20)
	v_mov_b64_e32 v[66:67], v[18:19]
	v_mov_b64_e32 v[50:51], v[18:19]
	s_mov_b32 s39, 0
	v_ashrrev_i32_e32 v149, 31, v148
	v_mov_b32_e32 v153, 0
	s_mov_b64 s[0:1], 0
	v_mov_b64_e32 v[32:33], v[16:17]
	v_mov_b64_e32 v[30:31], v[14:15]
	v_mov_b64_e32 v[28:29], v[12:13]
	v_mov_b64_e32 v[26:27], v[10:11]
	v_mov_b64_e32 v[24:25], v[8:9]
	v_mov_b64_e32 v[22:23], v[6:7]
	v_mov_b64_e32 v[20:21], v[4:5]
	v_mov_b32_e32 v152, 0
	v_mov_b32_e32 v243, 0
	v_mov_b32_e32 v244, 0
	v_mov_b64_e32 v[64:65], v[16:17]
	v_mov_b64_e32 v[62:63], v[14:15]
	v_mov_b64_e32 v[60:61], v[12:13]
	v_mov_b64_e32 v[58:59], v[10:11]
	v_mov_b64_e32 v[56:57], v[8:9]
	v_mov_b64_e32 v[54:55], v[6:7]
	v_mov_b64_e32 v[52:53], v[4:5]
	v_mov_b64_e32 v[48:49], v[16:17]
	v_mov_b64_e32 v[46:47], v[14:15]
	v_mov_b64_e32 v[44:45], v[12:13]
	v_mov_b64_e32 v[42:43], v[10:11]
	v_mov_b64_e32 v[40:41], v[8:9]
	v_mov_b64_e32 v[38:39], v[6:7]
	v_mov_b64_e32 v[36:37], v[4:5]
	s_barrier
	s_waitcnt vmcnt(11)
	ds_write_b128 v239, v[100:103]
	s_waitcnt vmcnt(10)
	ds_write_b128 v239, v[104:107] offset:4608
	s_waitcnt vmcnt(9)
	ds_write_b128 v239, v[112:115] offset:18432
	s_waitcnt vmcnt(8)
	ds_write_b128 v239, v[128:131] offset:23040
	s_waitcnt lgkmcnt(0)
	s_barrier
	v_mov_b32_e32 v223, v219
	v_mov_b32_e32 v254, v239
	v_mov_b32_e32 v224, 0
	v_mov_b32_e32 v225, 0
	v_mov_b32_e32 v226, 0
	v_mov_b32_e32 v227, 0
	v_mov_b32_e32 v228, 0
	v_mov_b32_e32 v229, 0
	v_mov_b32_e32 v230, 0
	v_mov_b32_e32 v231, 0
	v_mov_b32_e32 v232, 0
	v_mov_b32_e32 v233, 0
	v_mov_b32_e32 v234, 0
	v_mov_b32_e32 v235, 0
	v_mov_b32_e32 v236, 0
	v_mov_b32_e32 v237, 0
	v_mov_b32_e32 v238, 0
	v_mov_b32_e32 v239, 0
	v_mov_b32_e32 v244, 0
	v_mov_b32_e32 v245, 0
	v_mov_b32_e32 v246, 0
	v_mov_b32_e32 v247, 0
	v_mov_b32_e32 v248, 0
	v_mov_b32_e32 v249, 0
	v_mov_b32_e32 v250, 0
	v_mov_b32_e32 v251, 0
	v_mov_b32_e32 v243, 0
	v_lshrrev_b32_e32 v218, 4, v222
	v_xor_b32_e32 v218, v218, v222
	v_and_b32_e32 v218, 1, v218
	v_cmp_eq_u32_e32 vcc, 0, v218
	v_mov_b32_e32 v219, 0x3f803f80
	v_cndmask_b32_e32 v218, 0, v219, vcc
	v_mov_b32_e32 v219, v218
	v_mov_b32_e32 v220, v218
	v_mov_b32_e32 v221, v218
.LBB0_766:
	s_add_i32 s22, s39, 2
	s_cmp_lt_u32 s22, s38
	s_cselect_b64 s[10:11], -1, 0
	s_cmp_ge_u32 s22, s38
	s_cselect_b64 s[12:13], -1, 0
	ds_read_b128 v[186:189], v240
	ds_read_b128 v[190:193], v240 offset:4608
	ds_read_b128 v[194:197], v240 offset:32
	ds_read_b128 v[198:201], v240 offset:4640
	ds_read_b128 v[202:205], v240 offset:64
	ds_read_b128 v[206:209], v240 offset:4672
	ds_read_b128 v[210:213], v240 offset:96
	ds_read_b128 v[214:217], v240 offset:4704
	s_and_b64 vcc, exec, s[12:13]
	s_cbranch_vccnz .Lat_noload_a
	s_add_u32 s4, s0, 0x7275000
	s_addc_u32 s5, s1, 0
	s_add_u32 s6, s0, 0x72ad000
	s_addc_u32 s7, s1, 0
	v_lshl_add_u64 v[68:69], v[150:151], 0, s[4:5]
	v_lshl_add_u64 v[70:71], v[150:151], 0, s[6:7]
	global_load_dwordx4 v[100:103], v[68:69], off offset:1536
	global_load_dwordx4 v[112:115], v[68:69], off offset:2048
	global_load_dwordx4 v[104:107], v[70:71], off offset:1536
	global_load_dwordx4 v[128:131], v[70:71], off offset:2048
.Lat_noload_a:
	s_waitcnt vmcnt(8) lgkmcnt(0)
	v_mfma_f32_32x32x16_bf16 v[68:83], v[186:189], v[120:123], v[224:239]
	ds_read_b64_tr_b16 v[186:187], v241 offset:18432
	ds_read_b64_tr_b16 v[188:189], v241 offset:19584
	v_mfma_f32_32x32x16_bf16 v[84:99], v[190:193], v[120:123], v[224:239]
	ds_read_b64_tr_b16 v[190:191], v241 offset:18496
	ds_read_b64_tr_b16 v[192:193], v241 offset:19648
	v_mfma_f32_32x32x16_bf16 v[68:83], v[194:197], v[108:111], v[68:83]
	ds_read_b64_tr_b16 v[194:195], v241 offset:20736
	ds_read_b64_tr_b16 v[196:197], v241 offset:21888
	v_mfma_f32_32x32x16_bf16 v[84:99], v[198:201], v[108:111], v[84:99]
	ds_read_b64_tr_b16 v[198:199], v241 offset:20800
	ds_read_b64_tr_b16 v[200:201], v241 offset:21952
	v_mfma_f32_32x32x16_bf16 v[154:169], v[202:205], v[116:119], v[224:239]
	ds_read_b64_tr_b16 v[202:203], v242 offset:23040
	ds_read_b64_tr_b16 v[204:205], v242 offset:24192
	v_mfma_f32_32x32x16_bf16 v[170:185], v[206:209], v[116:119], v[224:239]
	ds_read_b64_tr_b16 v[206:207], v242 offset:23104
	ds_read_b64_tr_b16 v[208:209], v242 offset:24256
	s_nop 0
	v_exp_f32_e32 v68, v68
	v_exp_f32_e32 v69, v69
	v_exp_f32_e32 v70, v70
	v_exp_f32_e32 v71, v71
	v_mfma_f32_32x32x16_bf16 v[154:169], v[210:213], v[124:127], v[154:169]
	ds_read_b64_tr_b16 v[210:211], v242 offset:25344
	ds_read_b64_tr_b16 v[212:213], v242 offset:26496
	v_exp_f32_e32 v72, v72
	v_exp_f32_e32 v73, v73
	v_exp_f32_e32 v74, v74
	v_exp_f32_e32 v75, v75
	v_cvt_pk_bf16_f32 v68, v68, v69
	v_cvt_pk_bf16_f32 v69, v70, v71
	v_cvt_pk_bf16_f32 v70, v72, v73
	v_cvt_pk_bf16_f32 v71, v74, v75
	v_mfma_f32_32x32x16_bf16 v[170:185], v[214:217], v[124:127], v[170:185]
	ds_read_b64_tr_b16 v[214:215], v242 offset:25408
	ds_read_b64_tr_b16 v[216:217], v242 offset:26560
	v_exp_f32_e32 v154, v154
	v_exp_f32_e32 v155, v155
	s_waitcnt lgkmcnt(12)
	v_mfma_f32_32x32x16_bf16 v[4:19], v[186:189], v[68:71], v[4:19]
	v_exp_f32_e32 v156, v156
	v_exp_f32_e32 v157, v157
	v_exp_f32_e32 v158, v158
	v_mfma_f32_32x32x16_bf16 v[20:35], v[190:193], v[68:71], v[20:35]
	v_exp_f32_e32 v159, v159
	v_exp_f32_e32 v160, v160
	v_exp_f32_e32 v161, v161
	v_mfma_f32_16x16x32_bf16 v[244:247], v[68:71], v[218:221], v[244:247]
	v_cvt_pk_bf16_f32 v154, v154, v155
	v_cvt_pk_bf16_f32 v155, v156, v157
	v_cvt_pk_bf16_f32 v156, v158, v159
	v_cvt_pk_bf16_f32 v157, v160, v161
	v_exp_f32_e32 v76, v76
	v_exp_f32_e32 v77, v77
	v_mfma_f32_32x32x16_bf16 v[36:51], v[186:189], v[154:157], v[36:51]
	v_exp_f32_e32 v78, v78
	v_exp_f32_e32 v79, v79
	v_exp_f32_e32 v80, v80
	v_mfma_f32_32x32x16_bf16 v[52:67], v[190:193], v[154:157], v[52:67]
	v_exp_f32_e32 v81, v81
	v_exp_f32_e32 v82, v82
	v_exp_f32_e32 v83, v83
	v_mfma_f32_16x16x32_bf16 v[248:251], v[154:157], v[218:221], v[248:251]
	v_cvt_pk_bf16_f32 v76, v76, v77
	v_cvt_pk_bf16_f32 v77, v78, v79
	v_cvt_pk_bf16_f32 v78, v80, v81
	v_cvt_pk_bf16_f32 v79, v82, v83
	v_exp_f32_e32 v162, v162
	v_exp_f32_e32 v163, v163
	s_waitcnt lgkmcnt(8)
	v_mfma_f32_32x32x16_bf16 v[4:19], v[194:197], v[76:79], v[4:19]
	v_exp_f32_e32 v164, v164
	v_exp_f32_e32 v165, v165
	v_exp_f32_e32 v166, v166
	v_mfma_f32_32x32x16_bf16 v[20:35], v[198:201], v[76:79], v[20:35]
	v_exp_f32_e32 v167, v167
	v_exp_f32_e32 v168, v168
	v_exp_f32_e32 v169, v169
	v_mfma_f32_16x16x32_bf16 v[244:247], v[76:79], v[218:221], v[244:247]
	v_cvt_pk_bf16_f32 v162, v162, v163
	v_cvt_pk_bf16_f32 v163, v164, v165
	v_cvt_pk_bf16_f32 v164, v166, v167
	v_cvt_pk_bf16_f32 v165, v168, v169
	v_exp_f32_e32 v84, v84
	v_exp_f32_e32 v85, v85
	v_mfma_f32_32x32x16_bf16 v[36:51], v[194:197], v[162:165], v[36:51]
	v_exp_f32_e32 v86, v86
	v_exp_f32_e32 v87, v87
	v_exp_f32_e32 v88, v88
	v_mfma_f32_32x32x16_bf16 v[52:67], v[198:201], v[162:165], v[52:67]
	v_exp_f32_e32 v89, v89
	v_exp_f32_e32 v90, v90
	v_exp_f32_e32 v91, v91
	v_mfma_f32_16x16x32_bf16 v[248:251], v[162:165], v[218:221], v[248:251]
	v_cvt_pk_bf16_f32 v84, v84, v85
	v_cvt_pk_bf16_f32 v85, v86, v87
	v_cvt_pk_bf16_f32 v86, v88, v89
	v_cvt_pk_bf16_f32 v87, v90, v91
	v_exp_f32_e32 v170, v170
	v_exp_f32_e32 v171, v171
	s_waitcnt lgkmcnt(4)
	v_mfma_f32_32x32x16_bf16 v[4:19], v[202:205], v[84:87], v[4:19]
	v_exp_f32_e32 v172, v172
	v_exp_f32_e32 v173, v173
	v_exp_f32_e32 v174, v174
	v_mfma_f32_32x32x16_bf16 v[20:35], v[206:209], v[84:87], v[20:35]
	v_exp_f32_e32 v175, v175
	v_exp_f32_e32 v176, v176
	v_exp_f32_e32 v177, v177
	v_mfma_f32_16x16x32_bf16 v[244:247], v[84:87], v[218:221], v[244:247]
	v_cvt_pk_bf16_f32 v170, v170, v171
	v_cvt_pk_bf16_f32 v171, v172, v173
	v_cvt_pk_bf16_f32 v172, v174, v175
	v_cvt_pk_bf16_f32 v173, v176, v177
	v_exp_f32_e32 v92, v92
	v_exp_f32_e32 v93, v93
	v_mfma_f32_32x32x16_bf16 v[36:51], v[202:205], v[170:173], v[36:51]
	v_exp_f32_e32 v94, v94
	v_exp_f32_e32 v95, v95
	v_exp_f32_e32 v96, v96
	v_mfma_f32_32x32x16_bf16 v[52:67], v[206:209], v[170:173], v[52:67]
	v_exp_f32_e32 v97, v97
	v_exp_f32_e32 v98, v98
	v_exp_f32_e32 v99, v99
	v_mfma_f32_16x16x32_bf16 v[248:251], v[170:173], v[218:221], v[248:251]
	v_cvt_pk_bf16_f32 v92, v92, v93
	v_cvt_pk_bf16_f32 v93, v94, v95
	v_cvt_pk_bf16_f32 v94, v96, v97
	v_cvt_pk_bf16_f32 v95, v98, v99
	v_exp_f32_e32 v178, v178
	v_exp_f32_e32 v179, v179
	s_waitcnt lgkmcnt(0)
	v_mfma_f32_32x32x16_bf16 v[4:19], v[210:213], v[92:95], v[4:19]
	v_exp_f32_e32 v180, v180
	v_exp_f32_e32 v181, v181
	v_exp_f32_e32 v182, v182
	v_mfma_f32_32x32x16_bf16 v[20:35], v[214:217], v[92:95], v[20:35]
	v_exp_f32_e32 v183, v183
	v_exp_f32_e32 v184, v184
	v_exp_f32_e32 v185, v185
	v_mfma_f32_16x16x32_bf16 v[244:247], v[92:95], v[218:221], v[244:247]
	v_cvt_pk_bf16_f32 v178, v178, v179
	v_cvt_pk_bf16_f32 v179, v180, v181
	v_cvt_pk_bf16_f32 v180, v182, v183
	v_cvt_pk_bf16_f32 v181, v184, v185
	s_nop 1
	v_mfma_f32_16x16x32_bf16 v[248:251], v[178:181], v[218:221], v[248:251]
	v_mfma_f32_32x32x16_bf16 v[36:51], v[210:213], v[178:181], v[36:51]
	v_mfma_f32_32x32x16_bf16 v[52:67], v[214:217], v[178:181], v[52:67]
	s_nop 5
	v_max3_f32 v68, v244, v245, v246
	v_max3_f32 v68, v68, v247, v248
	v_max3_f32 v68, v68, v249, v250
	v_max_f32_e32 v68, v68, v251
	v_cmp_lt_f32_e32 vcc, 0x49800000, v68
	s_cbranch_vccz .Lat_norescale_a
	v_bfe_u32 v78, v222, 2, 2
	v_lshlrev_b32_e32 v78, 6, v78
	v_bfe_u32 v79, v222, 4, 1
	v_lshl_or_b32 v78, v79, 2, v78
	ds_bpermute_b32 v68, v78, v244
	ds_bpermute_b32 v69, v78, v245
	ds_bpermute_b32 v70, v78, v246
	ds_bpermute_b32 v71, v78, v247
	ds_bpermute_b32 v72, v78, v248
	ds_bpermute_b32 v73, v78, v249
	ds_bpermute_b32 v74, v78, v250
	ds_bpermute_b32 v75, v78, v251
	v_and_b32_e32 v79, 3, v222
	s_waitcnt lgkmcnt(0)
	v_cmp_eq_u32_e32 vcc, 1, v79
	v_cndmask_b32_e32 v76, v68, v69, vcc
	v_cndmask_b32_e32 v77, v72, v73, vcc
	v_cmp_eq_u32_e32 vcc, 2, v79
	v_cndmask_b32_e32 v76, v76, v70, vcc
	v_cndmask_b32_e32 v77, v77, v74, vcc
	v_cmp_eq_u32_e32 vcc, 3, v79
	v_cndmask_b32_e32 v76, v76, v71, vcc
	v_cndmask_b32_e32 v77, v77, v75, vcc
	v_max_f32_e32 v80, v76, v77
	v_log_f32_e32 v80, v80
	s_nop 0
	v_max_f32_e32 v80, 0, v80
	v_add_f32_e32 v243, v243, v80
	v_exp_f32_e64 v82, -v80
	v_xor_b32_e32 v224, 0x80000000, v243
	v_mov_b32_e32 v225, v224
	v_mov_b32_e32 v226, v224
	v_mov_b32_e32 v227, v224
	v_mov_b32_e32 v228, v224
	v_mov_b32_e32 v229, v224
	v_mov_b32_e32 v230, v224
	v_mov_b32_e32 v231, v224
	v_mov_b32_e32 v232, v224
	v_mov_b32_e32 v233, v224
	v_mov_b32_e32 v234, v224
	v_mov_b32_e32 v235, v224
	v_mov_b32_e32 v236, v224
	v_mov_b32_e32 v237, v224
	v_mov_b32_e32 v238, v224
	v_mov_b32_e32 v239, v224
	v_bfe_u32 v84, v222, 4, 2
	v_lshlrev_b32_e32 v84, 4, v84
	v_and_b32_e32 v85, 1, v222
	v_lshl_or_b32 v84, v85, 6, v84
	v_add_u32_e32 v85, 4, v84
	v_add_u32_e32 v86, 8, v84
	v_add_u32_e32 v87, 12, v84
	ds_bpermute_b32 v88, v84, v82
	ds_bpermute_b32 v89, v85, v82
	ds_bpermute_b32 v90, v86, v82
	ds_bpermute_b32 v91, v87, v82
	v_pk_mul_f32 v[4:5], v[4:5], v[82:83] op_sel_hi:[1,0]
	v_pk_mul_f32 v[6:7], v[6:7], v[82:83] op_sel_hi:[1,0]
	v_pk_mul_f32 v[8:9], v[8:9], v[82:83] op_sel_hi:[1,0]
	v_pk_mul_f32 v[10:11], v[10:11], v[82:83] op_sel_hi:[1,0]
	v_pk_mul_f32 v[12:13], v[12:13], v[82:83] op_sel_hi:[1,0]
	v_pk_mul_f32 v[14:15], v[14:15], v[82:83] op_sel_hi:[1,0]
	v_pk_mul_f32 v[16:17], v[16:17], v[82:83] op_sel_hi:[1,0]
	v_pk_mul_f32 v[18:19], v[18:19], v[82:83] op_sel_hi:[1,0]
	v_pk_mul_f32 v[20:21], v[20:21], v[82:83] op_sel_hi:[1,0]
	v_pk_mul_f32 v[22:23], v[22:23], v[82:83] op_sel_hi:[1,0]
	v_pk_mul_f32 v[24:25], v[24:25], v[82:83] op_sel_hi:[1,0]
	v_pk_mul_f32 v[26:27], v[26:27], v[82:83] op_sel_hi:[1,0]
	v_pk_mul_f32 v[28:29], v[28:29], v[82:83] op_sel_hi:[1,0]
	v_pk_mul_f32 v[30:31], v[30:31], v[82:83] op_sel_hi:[1,0]
	v_pk_mul_f32 v[32:33], v[32:33], v[82:83] op_sel_hi:[1,0]
	v_pk_mul_f32 v[34:35], v[34:35], v[82:83] op_sel_hi:[1,0]
	v_pk_mul_f32 v[36:37], v[36:37], v[82:83] op_sel_hi:[1,0]
	v_pk_mul_f32 v[38:39], v[38:39], v[82:83] op_sel_hi:[1,0]
	v_pk_mul_f32 v[40:41], v[40:41], v[82:83] op_sel_hi:[1,0]
	v_pk_mul_f32 v[42:43], v[42:43], v[82:83] op_sel_hi:[1,0]
	v_pk_mul_f32 v[44:45], v[44:45], v[82:83] op_sel_hi:[1,0]
	v_pk_mul_f32 v[46:47], v[46:47], v[82:83] op_sel_hi:[1,0]
	v_pk_mul_f32 v[48:49], v[48:49], v[82:83] op_sel_hi:[1,0]
	v_pk_mul_f32 v[50:51], v[50:51], v[82:83] op_sel_hi:[1,0]
	v_pk_mul_f32 v[52:53], v[52:53], v[82:83] op_sel_hi:[1,0]
	v_pk_mul_f32 v[54:55], v[54:55], v[82:83] op_sel_hi:[1,0]
	v_pk_mul_f32 v[56:57], v[56:57], v[82:83] op_sel_hi:[1,0]
	v_pk_mul_f32 v[58:59], v[58:59], v[82:83] op_sel_hi:[1,0]
	v_pk_mul_f32 v[60:61], v[60:61], v[82:83] op_sel_hi:[1,0]
	v_pk_mul_f32 v[62:63], v[62:63], v[82:83] op_sel_hi:[1,0]
	v_pk_mul_f32 v[64:65], v[64:65], v[82:83] op_sel_hi:[1,0]
	v_pk_mul_f32 v[66:67], v[66:67], v[82:83] op_sel_hi:[1,0]
	s_waitcnt lgkmcnt(0)
	v_mul_f32_e32 v244, v244, v88
	v_mul_f32_e32 v248, v248, v88
	v_mul_f32_e32 v245, v245, v89
	v_mul_f32_e32 v249, v249, v89
	v_mul_f32_e32 v246, v246, v90
	v_mul_f32_e32 v250, v250, v90
	v_mul_f32_e32 v247, v247, v91
	v_mul_f32_e32 v251, v251, v91

.Lat_mid_w:
	ds_write_b128 v254, v[132:135] offset:9216
	ds_write_b128 v254, v[136:139] offset:13824
	ds_write_b128 v254, v[140:143] offset:27648
	ds_write_b128 v254, v[144:147] offset:32256
	s_waitcnt lgkmcnt(0)
	s_barrier
	ds_read_b128 v[186:189], v240 offset:9216
	ds_read_b128 v[190:193], v240 offset:13824
	ds_read_b128 v[194:197], v240 offset:9248
	ds_read_b128 v[198:201], v240 offset:13856
	ds_read_b128 v[202:205], v240 offset:9280
	ds_read_b128 v[206:209], v240 offset:13888
	ds_read_b128 v[210:213], v240 offset:9312
	ds_read_b128 v[214:217], v240 offset:13920
	s_add_i32 s4, s39, 3
	s_cmp_ge_u32 s4, s38
	s_cbranch_scc1 .Lat_noload_b
	s_add_u32 s4, s0, 0x72e5000
	s_addc_u32 s5, s1, 0
	s_add_u32 s6, s0, 0x731d000
	s_addc_u32 s7, s1, 0
	v_lshl_add_u64 v[68:69], v[150:151], 0, s[4:5]
	v_lshl_add_u64 v[70:71], v[150:151], 0, s[6:7]
	global_load_dwordx4 v[132:135], v[68:69], off offset:1536
	global_load_dwordx4 v[140:143], v[68:69], off offset:2048
	global_load_dwordx4 v[136:139], v[70:71], off offset:1536
	global_load_dwordx4 v[144:147], v[70:71], off offset:2048
.Lat_noload_b:
	s_waitcnt vmcnt(8) lgkmcnt(0)
	v_mfma_f32_32x32x16_bf16 v[68:83], v[186:189], v[120:123], v[224:239]
	ds_read_b64_tr_b16 v[186:187], v241 offset:27648
	ds_read_b64_tr_b16 v[188:189], v241 offset:28800
	v_mfma_f32_32x32x16_bf16 v[84:99], v[190:193], v[120:123], v[224:239]
	ds_read_b64_tr_b16 v[190:191], v241 offset:27712
	ds_read_b64_tr_b16 v[192:193], v241 offset:28864
	v_mfma_f32_32x32x16_bf16 v[68:83], v[194:197], v[108:111], v[68:83]
	ds_read_b64_tr_b16 v[194:195], v241 offset:29952
	ds_read_b64_tr_b16 v[196:197], v241 offset:31104
	v_mfma_f32_32x32x16_bf16 v[84:99], v[198:201], v[108:111], v[84:99]
	ds_read_b64_tr_b16 v[198:199], v241 offset:30016
	ds_read_b64_tr_b16 v[200:201], v241 offset:31168
	v_mfma_f32_32x32x16_bf16 v[154:169], v[202:205], v[116:119], v[224:239]
	ds_read_b64_tr_b16 v[202:203], v242 offset:32256
	ds_read_b64_tr_b16 v[204:205], v242 offset:33408
	v_mfma_f32_32x32x16_bf16 v[170:185], v[206:209], v[116:119], v[224:239]
	ds_read_b64_tr_b16 v[206:207], v242 offset:32320
	ds_read_b64_tr_b16 v[208:209], v242 offset:33472
	s_nop 0
	v_exp_f32_e32 v68, v68
	v_exp_f32_e32 v69, v69
	v_exp_f32_e32 v70, v70
	v_exp_f32_e32 v71, v71
	v_mfma_f32_32x32x16_bf16 v[154:169], v[210:213], v[124:127], v[154:169]
	ds_read_b64_tr_b16 v[210:211], v242 offset:34560
	ds_read_b64_tr_b16 v[212:213], v242 offset:35712
	v_exp_f32_e32 v72, v72
	v_exp_f32_e32 v73, v73
	v_exp_f32_e32 v74, v74
	v_exp_f32_e32 v75, v75
	v_cvt_pk_bf16_f32 v68, v68, v69
	v_cvt_pk_bf16_f32 v69, v70, v71
	v_cvt_pk_bf16_f32 v70, v72, v73
	v_cvt_pk_bf16_f32 v71, v74, v75
	v_mfma_f32_32x32x16_bf16 v[170:185], v[214:217], v[124:127], v[170:185]
	ds_read_b64_tr_b16 v[214:215], v242 offset:34624
	ds_read_b64_tr_b16 v[216:217], v242 offset:35776
	v_exp_f32_e32 v154, v154
	v_exp_f32_e32 v155, v155
	s_waitcnt lgkmcnt(12)
	v_mfma_f32_32x32x16_bf16 v[4:19], v[186:189], v[68:71], v[4:19]
	v_exp_f32_e32 v156, v156
	v_exp_f32_e32 v157, v157
	v_exp_f32_e32 v158, v158
	v_mfma_f32_32x32x16_bf16 v[20:35], v[190:193], v[68:71], v[20:35]
	v_exp_f32_e32 v159, v159
	v_exp_f32_e32 v160, v160
	v_exp_f32_e32 v161, v161
	v_mfma_f32_16x16x32_bf16 v[244:247], v[68:71], v[218:221], v[244:247]
	v_cvt_pk_bf16_f32 v154, v154, v155
	v_cvt_pk_bf16_f32 v155, v156, v157
	v_cvt_pk_bf16_f32 v156, v158, v159
	v_cvt_pk_bf16_f32 v157, v160, v161
	v_exp_f32_e32 v76, v76
	v_exp_f32_e32 v77, v77
	v_mfma_f32_32x32x16_bf16 v[36:51], v[186:189], v[154:157], v[36:51]
	v_exp_f32_e32 v78, v78
	v_exp_f32_e32 v79, v79
	v_exp_f32_e32 v80, v80
	v_mfma_f32_32x32x16_bf16 v[52:67], v[190:193], v[154:157], v[52:67]
	v_exp_f32_e32 v81, v81
	v_exp_f32_e32 v82, v82
	v_exp_f32_e32 v83, v83
	v_mfma_f32_16x16x32_bf16 v[248:251], v[154:157], v[218:221], v[248:251]
	v_cvt_pk_bf16_f32 v76, v76, v77
	v_cvt_pk_bf16_f32 v77, v78, v79
	v_cvt_pk_bf16_f32 v78, v80, v81
	v_cvt_pk_bf16_f32 v79, v82, v83
	v_exp_f32_e32 v162, v162
	v_exp_f32_e32 v163, v163
	s_waitcnt lgkmcnt(8)
	v_mfma_f32_32x32x16_bf16 v[4:19], v[194:197], v[76:79], v[4:19]
	v_exp_f32_e32 v164, v164
	v_exp_f32_e32 v165, v165
	v_exp_f32_e32 v166, v166
	v_mfma_f32_32x32x16_bf16 v[20:35], v[198:201], v[76:79], v[20:35]
	v_exp_f32_e32 v167, v167
	v_exp_f32_e32 v168, v168
	v_exp_f32_e32 v169, v169
	v_mfma_f32_16x16x32_bf16 v[244:247], v[76:79], v[218:221], v[244:247]
	v_cvt_pk_bf16_f32 v162, v162, v163
	v_cvt_pk_bf16_f32 v163, v164, v165
	v_cvt_pk_bf16_f32 v164, v166, v167
	v_cvt_pk_bf16_f32 v165, v168, v169
	v_exp_f32_e32 v84, v84
	v_exp_f32_e32 v85, v85
	v_mfma_f32_32x32x16_bf16 v[36:51], v[194:197], v[162:165], v[36:51]
	v_exp_f32_e32 v86, v86
	v_exp_f32_e32 v87, v87
	v_exp_f32_e32 v88, v88
	v_mfma_f32_32x32x16_bf16 v[52:67], v[198:201], v[162:165], v[52:67]
	v_exp_f32_e32 v89, v89
	v_exp_f32_e32 v90, v90
	v_exp_f32_e32 v91, v91
	v_mfma_f32_16x16x32_bf16 v[248:251], v[162:165], v[218:221], v[248:251]
	v_cvt_pk_bf16_f32 v84, v84, v85
	v_cvt_pk_bf16_f32 v85, v86, v87
	v_cvt_pk_bf16_f32 v86, v88, v89
	v_cvt_pk_bf16_f32 v87, v90, v91
	v_exp_f32_e32 v170, v170
	v_exp_f32_e32 v171, v171
	s_waitcnt lgkmcnt(4)
	v_mfma_f32_32x32x16_bf16 v[4:19], v[202:205], v[84:87], v[4:19]
	v_exp_f32_e32 v172, v172
	v_exp_f32_e32 v173, v173
	v_exp_f32_e32 v174, v174
	v_mfma_f32_32x32x16_bf16 v[20:35], v[206:209], v[84:87], v[20:35]
	v_exp_f32_e32 v175, v175
	v_exp_f32_e32 v176, v176
	v_exp_f32_e32 v177, v177
	v_mfma_f32_16x16x32_bf16 v[244:247], v[84:87], v[218:221], v[244:247]
	v_cvt_pk_bf16_f32 v170, v170, v171
	v_cvt_pk_bf16_f32 v171, v172, v173
	v_cvt_pk_bf16_f32 v172, v174, v175
	v_cvt_pk_bf16_f32 v173, v176, v177
	v_exp_f32_e32 v92, v92
	v_exp_f32_e32 v93, v93
	v_mfma_f32_32x32x16_bf16 v[36:51], v[202:205], v[170:173], v[36:51]
	v_exp_f32_e32 v94, v94
	v_exp_f32_e32 v95, v95
	v_exp_f32_e32 v96, v96
	v_mfma_f32_32x32x16_bf16 v[52:67], v[206:209], v[170:173], v[52:67]
	v_exp_f32_e32 v97, v97
	v_exp_f32_e32 v98, v98
	v_exp_f32_e32 v99, v99
	v_mfma_f32_16x16x32_bf16 v[248:251], v[170:173], v[218:221], v[248:251]
	v_cvt_pk_bf16_f32 v92, v92, v93
	v_cvt_pk_bf16_f32 v93, v94, v95
	v_cvt_pk_bf16_f32 v94, v96, v97
	v_cvt_pk_bf16_f32 v95, v98, v99
	v_exp_f32_e32 v178, v178
	v_exp_f32_e32 v179, v179
	s_waitcnt lgkmcnt(0)
	v_mfma_f32_32x32x16_bf16 v[4:19], v[210:213], v[92:95], v[4:19]
	v_exp_f32_e32 v180, v180
	v_exp_f32_e32 v181, v181
	v_exp_f32_e32 v182, v182
	v_mfma_f32_32x32x16_bf16 v[20:35], v[214:217], v[92:95], v[20:35]
	v_exp_f32_e32 v183, v183
	v_exp_f32_e32 v184, v184
	v_exp_f32_e32 v185, v185
	v_mfma_f32_16x16x32_bf16 v[244:247], v[92:95], v[218:221], v[244:247]
	v_cvt_pk_bf16_f32 v178, v178, v179
	v_cvt_pk_bf16_f32 v179, v180, v181
	v_cvt_pk_bf16_f32 v180, v182, v183
	v_cvt_pk_bf16_f32 v181, v184, v185
	s_nop 1
	v_mfma_f32_16x16x32_bf16 v[248:251], v[178:181], v[218:221], v[248:251]
	v_mfma_f32_32x32x16_bf16 v[36:51], v[210:213], v[178:181], v[36:51]
	v_mfma_f32_32x32x16_bf16 v[52:67], v[214:217], v[178:181], v[52:67]
	s_nop 5
	v_max3_f32 v68, v244, v245, v246
	v_max3_f32 v68, v68, v247, v248
	v_max3_f32 v68, v68, v249, v250
	v_max_f32_e32 v68, v68, v251
	v_cmp_lt_f32_e32 vcc, 0x49800000, v68
	s_cbranch_vccz .Lat_norescale_b
	v_bfe_u32 v78, v222, 2, 2
	v_lshlrev_b32_e32 v78, 6, v78
	v_bfe_u32 v79, v222, 4, 1
	v_lshl_or_b32 v78, v79, 2, v78
	ds_bpermute_b32 v68, v78, v244
	ds_bpermute_b32 v69, v78, v245
	ds_bpermute_b32 v70, v78, v246
	ds_bpermute_b32 v71, v78, v247
	ds_bpermute_b32 v72, v78, v248
	ds_bpermute_b32 v73, v78, v249
	ds_bpermute_b32 v74, v78, v250
	ds_bpermute_b32 v75, v78, v251
	v_and_b32_e32 v79, 3, v222
	s_waitcnt lgkmcnt(0)
	v_cmp_eq_u32_e32 vcc, 1, v79
	v_cndmask_b32_e32 v76, v68, v69, vcc
	v_cndmask_b32_e32 v77, v72, v73, vcc
	v_cmp_eq_u32_e32 vcc, 2, v79
	v_cndmask_b32_e32 v76, v76, v70, vcc
	v_cndmask_b32_e32 v77, v77, v74, vcc
	v_cmp_eq_u32_e32 vcc, 3, v79
	v_cndmask_b32_e32 v76, v76, v71, vcc
	v_cndmask_b32_e32 v77, v77, v75, vcc
	v_max_f32_e32 v80, v76, v77
	v_log_f32_e32 v80, v80
	s_nop 0
	v_max_f32_e32 v80, 0, v80
	v_add_f32_e32 v243, v243, v80
	v_exp_f32_e64 v82, -v80
	v_xor_b32_e32 v224, 0x80000000, v243
	v_mov_b32_e32 v225, v224
	v_mov_b32_e32 v226, v224
	v_mov_b32_e32 v227, v224
	v_mov_b32_e32 v228, v224
	v_mov_b32_e32 v229, v224
	v_mov_b32_e32 v230, v224
	v_mov_b32_e32 v231, v224
	v_mov_b32_e32 v232, v224
	v_mov_b32_e32 v233, v224
	v_mov_b32_e32 v234, v224
	v_mov_b32_e32 v235, v224
	v_mov_b32_e32 v236, v224
	v_mov_b32_e32 v237, v224
	v_mov_b32_e32 v238, v224
	v_mov_b32_e32 v239, v224
	v_bfe_u32 v84, v222, 4, 2
	v_lshlrev_b32_e32 v84, 4, v84
	v_and_b32_e32 v85, 1, v222
	v_lshl_or_b32 v84, v85, 6, v84
	v_add_u32_e32 v85, 4, v84
	v_add_u32_e32 v86, 8, v84
	v_add_u32_e32 v87, 12, v84
	ds_bpermute_b32 v88, v84, v82
	ds_bpermute_b32 v89, v85, v82
	ds_bpermute_b32 v90, v86, v82
	ds_bpermute_b32 v91, v87, v82
	v_pk_mul_f32 v[4:5], v[4:5], v[82:83] op_sel_hi:[1,0]
	v_pk_mul_f32 v[6:7], v[6:7], v[82:83] op_sel_hi:[1,0]
	v_pk_mul_f32 v[8:9], v[8:9], v[82:83] op_sel_hi:[1,0]
	v_pk_mul_f32 v[10:11], v[10:11], v[82:83] op_sel_hi:[1,0]
	v_pk_mul_f32 v[12:13], v[12:13], v[82:83] op_sel_hi:[1,0]
	v_pk_mul_f32 v[14:15], v[14:15], v[82:83] op_sel_hi:[1,0]
	v_pk_mul_f32 v[16:17], v[16:17], v[82:83] op_sel_hi:[1,0]
	v_pk_mul_f32 v[18:19], v[18:19], v[82:83] op_sel_hi:[1,0]
	v_pk_mul_f32 v[20:21], v[20:21], v[82:83] op_sel_hi:[1,0]
	v_pk_mul_f32 v[22:23], v[22:23], v[82:83] op_sel_hi:[1,0]
	v_pk_mul_f32 v[24:25], v[24:25], v[82:83] op_sel_hi:[1,0]
	v_pk_mul_f32 v[26:27], v[26:27], v[82:83] op_sel_hi:[1,0]
	v_pk_mul_f32 v[28:29], v[28:29], v[82:83] op_sel_hi:[1,0]
	v_pk_mul_f32 v[30:31], v[30:31], v[82:83] op_sel_hi:[1,0]
	v_pk_mul_f32 v[32:33], v[32:33], v[82:83] op_sel_hi:[1,0]
	v_pk_mul_f32 v[34:35], v[34:35], v[82:83] op_sel_hi:[1,0]
	v_pk_mul_f32 v[36:37], v[36:37], v[82:83] op_sel_hi:[1,0]
	v_pk_mul_f32 v[38:39], v[38:39], v[82:83] op_sel_hi:[1,0]
	v_pk_mul_f32 v[40:41], v[40:41], v[82:83] op_sel_hi:[1,0]
	v_pk_mul_f32 v[42:43], v[42:43], v[82:83] op_sel_hi:[1,0]
	v_pk_mul_f32 v[44:45], v[44:45], v[82:83] op_sel_hi:[1,0]
	v_pk_mul_f32 v[46:47], v[46:47], v[82:83] op_sel_hi:[1,0]
	v_pk_mul_f32 v[48:49], v[48:49], v[82:83] op_sel_hi:[1,0]
	v_pk_mul_f32 v[50:51], v[50:51], v[82:83] op_sel_hi:[1,0]
	v_pk_mul_f32 v[52:53], v[52:53], v[82:83] op_sel_hi:[1,0]
	v_pk_mul_f32 v[54:55], v[54:55], v[82:83] op_sel_hi:[1,0]
	v_pk_mul_f32 v[56:57], v[56:57], v[82:83] op_sel_hi:[1,0]
	v_pk_mul_f32 v[58:59], v[58:59], v[82:83] op_sel_hi:[1,0]
	v_pk_mul_f32 v[60:61], v[60:61], v[82:83] op_sel_hi:[1,0]
	v_pk_mul_f32 v[62:63], v[62:63], v[82:83] op_sel_hi:[1,0]
	v_pk_mul_f32 v[64:65], v[64:65], v[82:83] op_sel_hi:[1,0]
	v_pk_mul_f32 v[66:67], v[66:67], v[82:83] op_sel_hi:[1,0]
	s_waitcnt lgkmcnt(0)
	v_mul_f32_e32 v244, v244, v88
	v_mul_f32_e32 v248, v248, v88
	v_mul_f32_e32 v245, v245, v89
	v_mul_f32_e32 v249, v249, v89
	v_mul_f32_e32 v246, v246, v90
	v_mul_f32_e32 v250, v250, v90
	v_mul_f32_e32 v247, v247, v91
	v_mul_f32_e32 v251, v251, v91
.Lat_norescale_b:
	s_andn2_b64 vcc, exec, s[10:11]
	s_cbranch_vccnz .Lat_nowrite_a
	s_waitcnt vmcnt(4)
	ds_write_b128 v254, v[100:103]
	ds_write_b128 v254, v[104:107] offset:4608
	ds_write_b128 v254, v[112:115] offset:18432
	ds_write_b128 v254, v[128:131] offset:23040
.Lat_nowrite_a:
	s_add_u32 s0, s0, 0xe0000
	s_addc_u32 s1, s1, 0
	s_andn2_b64 vcc, exec, s[12:13]
	s_waitcnt lgkmcnt(0)
	s_barrier
	s_cbranch_vccnz .Lat_more
	v_bfe_u32 v78, v222, 2, 2
	v_lshlrev_b32_e32 v78, 6, v78
	v_bfe_u32 v79, v222, 4, 1
	v_lshl_or_b32 v78, v79, 2, v78
	ds_bpermute_b32 v68, v78, v244
	ds_bpermute_b32 v69, v78, v245
	ds_bpermute_b32 v70, v78, v246
	ds_bpermute_b32 v71, v78, v247
	ds_bpermute_b32 v72, v78, v248
	ds_bpermute_b32 v73, v78, v249
	ds_bpermute_b32 v74, v78, v250
	ds_bpermute_b32 v75, v78, v251
	v_and_b32_e32 v79, 3, v222
	s_waitcnt lgkmcnt(0)
	v_cmp_eq_u32_e32 vcc, 1, v79
	v_cndmask_b32_e32 v76, v68, v69, vcc
	v_cndmask_b32_e32 v77, v72, v73, vcc
	v_cmp_eq_u32_e32 vcc, 2, v79
	v_cndmask_b32_e32 v76, v76, v70, vcc
	v_cndmask_b32_e32 v77, v77, v74, vcc
	v_cmp_eq_u32_e32 vcc, 3, v79
	v_cndmask_b32_e32 v76, v76, v71, vcc
	v_cndmask_b32_e32 v77, v77, v75, vcc
	v_mul_f32_e32 v152, 0.5, v76
	v_mul_f32_e32 v153, 0.5, v77
	v_mov_b32_e32 v219, v223
	v_mov_b32_e32 v218, 0x3f317218
	v_mov_b32_e32 v223, 0x358637bd
	v_mov_b32_e32 v224, 0x1000
	v_mov_b32_e32 v225, 0x2000
	v_mov_b32_e32 v226, 1
	v_mov_b32_e32 v227, 0x3727c5ac
	v_mov_b32_e32 v228, 0x3ecc95a3
	v_bfrev_b32_e32 v229, 0.5
	v_mov_b32_e32 v230, 0x41b17218
	v_mov_b32_e32 v231, 0x3e8293ee
	v_mov_b32_e32 v232, 0xfffff000
	v_mov_b32_e32 v233, 0x1c00
	v_mov_b32_e32 v234, 0x7f800000
	v_mov_b32_e32 v235, 0x7fc00000
	v_mov_b32_e32 v236, 0xff800000
	v_mov_b32_e32 v237, 0x1dc0000
	v_mov_b32_e32 v238, 0x1100
	s_branch .LBB0_541
